# first phase: layer-0 weight conversion rebalanced against the modulation GEMV (workgroups 0..63 convert half as many items)
# baseline (speedup 1.0000x reference)
.LBB0_88:
	v_readlane_b32 s0, v251, 36
	s_nop 1
	v_lshl_add_u32 v0, s0, 6, v64
	s_mov_b32 s0, s91
	s_cmp_lt_i32 s0, 0
	s_cbranch_scc1 .LBB0_156
	v_mbcnt_lo_u32_b32 v220, -1, 0
	v_mbcnt_hi_u32_b32 v220, -1, v220
	s_load_dword s1, s[64:65], 0x0
	s_add_u32 s2, s62, 0x1bee0000
	s_addc_u32 s3, s63, 0
	v_writelane_b32 v251, s2, 41
	v_writelane_b32 v251, s3, 42
	v_writelane_b32 v252, s56, 26
	v_writelane_b32 v252, s57, 27
	v_readlane_b32 s4, v251, 36
	s_lshl_b32 s0, s91, 3
	s_nop 0
	s_add_i32 s0, s0, s4
	s_mul_i32 s15, s4, 0x2100
	s_movk_i32 s14, 0x3800
	s_mov_b32 s12, 0
	s_waitcnt lgkmcnt(0)
	s_lshl_b32 s1, s1, 3
	s_cmp_lg_u32 s1, 0x800
	s_cbranch_scc1 .Lcvth_nobal
	s_cmp_gt_u32 s91, 63
	s_cbranch_scc1 .Lcvth_clsb
	s_movk_i32 s1, 0x200
	s_movk_i32 s14, 0x800
	s_branch .Lcvth_nobal
.Lcvth_clsb:
	s_addk_i32 s0, 0x600
	s_movk_i32 s1, 0x600
.Lcvth_nobal:
.Lcvth_entry:
	v_lshrrev_b32_e32 v100, 3, v220
	v_and_b32_e32 v101, 7, v220
	v_mul_u32_u24_e32 v102, 0x84, v100
	v_lshl_add_u32 v102, v101, 4, v102
	v_add_u32_e32 v102, s15, v102
	v_mul_u32_u24_e32 v103, 0x420, v101
	v_lshl_add_u32 v103, v100, 2, v103
	v_add_u32_e32 v103, s15, v103
	v_and_b32_e32 v104, 3, v100
	v_lshrrev_b32_e32 v105, 2, v100
	v_lshl_or_b32 v104, v105, 4, v104
	v_lshlrev_b32_e32 v105, 4, v101
